# grid barrier: acquire-side cache invalidate issued at arrival (non-leaders) / right after the write-back (XCD leader) so it overlaps the polling and top-level atomic round trips
# speedup vs baseline: 1.0192x; 1.0098x over previous
; DI unsigned xb_ld(unsigned* p) { return __hip_atomic_load(p, __ATOMIC_RELAXED, __HIP_MEMORY_SCOPE_AGENT); }
; DI unsigned xb_add(unsigned* p, unsigned v) { return __hip_atomic_fetch_add(p, v, __ATOMIC_RELAXED, __HIP_MEMORY_SCOPE_AGENT); }
; #define XB_SPIN(cond, bar) do { unsigned _sp = 0; while (cond) { __builtin_amdgcn_s_sleep(1); \
;     if ((++_sp & 255u) == 0u) { if (xb_ld(&(bar)[XB_TMO])) break; if (_sp > XB_SPIN_CAP) { atomicAdd(&(bar)[XB_TMO], 1u); break; } } } } while (0)
; DI void xcd_barrier(const XcdBarrier& b) {
;     ...
;     unsigned nloc = b.st[0], nx = b.st[1];
;     if (nloc == 0u) { xcd_barrier_complete(bar, b.x, nloc, nx); b.st[0] = nloc; b.st[1] = nx; }
;     const unsigned old = xb_add(&bar[XB_XSUB(b.x)], 1u);
;     const unsigned gen = old / nloc;
;     if (old + 1u == (gen + 1u) * nloc) {
;       __builtin_amdgcn_fence(__ATOMIC_RELEASE, "agent");
;       asm volatile("s_waitcnt vmcnt(0)" ::: "memory");
;       const unsigned og = xb_add(&bar[XB_TOP], 1u);
;       const unsigned tg = og / nx;
;       if (og + 1u == (tg + 1u) * nx) xb_add(&bar[XB_TOPGEN], 1u);
;       else XB_SPIN(xb_ld(&bar[XB_TOPGEN]) == tg, bar);
;       __builtin_amdgcn_fence(__ATOMIC_ACQUIRE, "agent");
;       xb_add(&bar[XB_XGEN(b.x)], 1u);
;       asm volatile("s_waitcnt vmcnt(0)" ::: "memory");
;     } else {
;       XB_SPIN(xb_ld(&bar[XB_XGEN(b.x)]) == gen, bar);
.LBB0_2090:
	s_or_b64 exec, exec, s[4:5]
	v_cvt_f32_u32_e32 v5, v3
	s_waitcnt vmcnt(0)
	v_readfirstlane_b32 s4, v4
	v_sub_u32_e32 v4, 0, v3
	v_rcp_iflag_f32_e32 v5, v5
	v_add_u32_e32 v6, s4, v0
	v_mul_f32_e32 v5, 0x4f7ffffe, v5
	v_cvt_u32_f32_e32 v5, v5
	v_mul_lo_u32 v0, v4, v5
	v_mul_hi_u32 v0, v5, v0
	v_add_u32_e32 v0, v5, v0
	v_mul_hi_u32 v0, v6, v0
	v_mul_lo_u32 v4, v0, v3
	v_sub_u32_e32 v4, v6, v4
	v_add_u32_e32 v5, 1, v0
	v_cmp_ge_u32_e32 vcc, v4, v3
	s_nop 1
	v_cndmask_b32_e32 v0, v0, v5, vcc
	v_sub_u32_e32 v5, v4, v3
	v_cndmask_b32_e32 v4, v4, v5, vcc
	v_add_u32_e32 v5, 1, v0
	v_cmp_ge_u32_e32 vcc, v4, v3
	v_add_u32_e32 v4, 1, v6
	s_nop 0
	v_cndmask_b32_e32 v0, v0, v5, vcc
	v_mul_lo_u32 v5, v3, v0
	v_add_u32_e32 v3, v5, v3
	v_cmp_ne_u32_e32 vcc, v4, v3
	s_and_saveexec_b64 s[4:5], vcc
	s_xor_b64 s[4:5], exec, s[4:5]
	s_cbranch_execz .LBB0_2104
	buffer_inv sc1
	v_readlane_b32 s6, v238, 19
	v_readlane_b32 s7, v238, 20
	s_waitcnt lgkmcnt(0)
	s_nop 3
	global_load_dword v2, v1, s[6:7] sc1
	s_waitcnt vmcnt(0)
	v_cmp_eq_u32_e32 vcc, v2, v0
	s_and_saveexec_b64 s[6:7], vcc
	s_cbranch_execz .LBB0_2103
	s_mov_b32 s18, 1
	s_mov_b64 s[8:9], 0
	s_branch .LBB0_2094

; DI unsigned xb_ld(unsigned* p) { return __hip_atomic_load(p, __ATOMIC_RELAXED, __HIP_MEMORY_SCOPE_AGENT); }
; #define XB_SPIN(cond, bar) do { unsigned _sp = 0; while (cond) { __builtin_amdgcn_s_sleep(1); \
;     if ((++_sp & 255u) == 0u) { if (xb_ld(&(bar)[XB_TMO])) break; if (_sp > XB_SPIN_CAP) { atomicAdd(&(bar)[XB_TMO], 1u); break; } } } } while (0)
; DI void xcd_barrier(const XcdBarrier& b) {
;     ...
;       XB_SPIN(xb_ld(&bar[XB_XGEN(b.x)]) == gen, bar);
;       __builtin_amdgcn_fence(__ATOMIC_ACQUIRE, "agent");
;       asm volatile("s_waitcnt vmcnt(0)" ::: "memory");
.LBB0_2103:
	s_or_b64 exec, exec, s[6:7]
	s_waitcnt vmcnt(0)
	s_waitcnt vmcnt(0)

; DI unsigned xb_add(unsigned* p, unsigned v) { return __hip_atomic_fetch_add(p, v, __ATOMIC_RELAXED, __HIP_MEMORY_SCOPE_AGENT); }
; DI void xcd_barrier(const XcdBarrier& b) {
;     ...
;     if (old + 1u == (gen + 1u) * nloc) {
;       __builtin_amdgcn_fence(__ATOMIC_RELEASE, "agent");
;       asm volatile("s_waitcnt vmcnt(0)" ::: "memory");
;       const unsigned og = xb_add(&bar[XB_TOP], 1u);
.LBB0_2105:
	s_mov_b64 s[4:5], exec
	buffer_wbl2 sc1
	s_waitcnt lgkmcnt(0)
	s_waitcnt vmcnt(0)
	buffer_inv sc1
	v_mbcnt_lo_u32_b32 v0, s4, 0
	v_mbcnt_hi_u32_b32 v0, s5, v0
	v_cmp_eq_u32_e32 vcc, 0, v0
	s_and_saveexec_b64 s[6:7], vcc
	s_cbranch_execz .LBB0_2107
	s_bcnt1_i32_b64 s4, s[4:5]
	v_mov_b32_e32 v3, s4
	v_readlane_b32 s4, v238, 21
	v_readlane_b32 s5, v238, 22
	s_nop 4
	global_atomic_add v3, v1, v3, s[4:5] sc0

; DI unsigned xb_add(unsigned* p, unsigned v) { return __hip_atomic_fetch_add(p, v, __ATOMIC_RELAXED, __HIP_MEMORY_SCOPE_AGENT); }
; DI void xcd_barrier(const XcdBarrier& b) {
;     ...
;       __builtin_amdgcn_fence(__ATOMIC_ACQUIRE, "agent");
;       xb_add(&bar[XB_XGEN(b.x)], 1u);
;       asm volatile("s_waitcnt vmcnt(0)" ::: "memory");
.LBB0_2121:
	s_or_b64 exec, exec, s[4:5]
	s_mov_b64 s[4:5], exec
	v_mbcnt_lo_u32_b32 v0, s4, 0
	v_mbcnt_hi_u32_b32 v0, s5, v0
	v_cmp_eq_u32_e32 vcc, 0, v0
	s_waitcnt vmcnt(0)
	s_and_saveexec_b64 s[6:7], vcc
	s_cbranch_execnz .LBB0_2122
	s_getpc_b64 s[98:99]
